# e51 + S5-table workgroups run their rmsnorm rows first (after the GEMV counter) and the compute-only table item last
# baseline (speedup 1.0000x reference)
; #define LAS __attribute__((address_space(3)))
; #define SUB(i, ...) do { if (PROBE_PH == phk && PROBE_SUB == (i)) { __syncthreads(); tp0 = __builtin_amdgcn_s_memrealtime(); } __VA_ARGS__ if (PROBE_PH == phk && PROBE_SUB == (i)) { asm volatile("s_waitcnt vmcnt(0)" ::: "memory"); __syncthreads(); tp1 = __builtin_amdgcn_s_memrealtime(); } } while (0)
; __global__ void __launch_bounds__(NTHREADS, 2) mk_fwd(Args a) {
;     ...
;         SUB(0, if (vcu < 128) ssm_tables((LAS float*)lds, vcu, a.in[10], a.in[11], a.in[12], a.in[13], a.in[14], a.in[15], a.in[16], (f16*)(a.ws + WS_PG), (f16*)(a.ws + WS_QG), (f16*)(a.ws + WS_KTH)); );
;         { pg8::ListOrder S; S.init(32, 1, 8, G, vcu >= 128 && vcu < 160 ? vcu - 128 : 1 << 20);
;           EpiWp E{(f16*)(a.ws + WS_WIN)};
;           SUB(3, pg8::gemm_phase<CfgWp, EpiWp, pg8::ListOrder, true, true>(lds, (const char*)(a.ws + WS_WPOOL), (const char*)(a.ws + WS_WRAW), S, E); ); }
;         SUB(1, norm_rows(vcu * NWAVES + wave, lane, a.in[0], a.in[2], a.in[6], (const float*)(a.ws + WS_MOD), (f16*)(a.ws + WS_H)); );
.LBB0_165:
	s_cmp_eq_u32 s100, 7
	s_cbranch_scc1 .Lp1_seam
	s_and_saveexec_b64 s[2:3], s[82:83]
	s_cbranch_execz .Lp1_waited
	s_and_b32 s98, s81, 0xffffffe0
	s_cmpk_eq_i32 s98, 0x80
	s_mov_b32 s98, 0xe000
	s_movk_i32 s101, 0xc0
	s_cbranch_scc0 .Lp1_wsel
	s_movk_i32 s98, 0x3500
	s_movk_i32 s101, 1

; #define LAS __attribute__((address_space(3)))
; #define SUB(i, ...) do { if (PROBE_PH == phk && PROBE_SUB == (i)) { __syncthreads(); tp0 = __builtin_amdgcn_s_memrealtime(); } __VA_ARGS__ if (PROBE_PH == phk && PROBE_SUB == (i)) { asm volatile("s_waitcnt vmcnt(0)" ::: "memory"); __syncthreads(); tp1 = __builtin_amdgcn_s_memrealtime(); } } while (0)
; __global__ void __launch_bounds__(NTHREADS, 2) mk_fwd(Args a) {
;     ...
;         SUB(0, if (vcu < 128) ssm_tables((LAS float*)lds, vcu, a.in[10], a.in[11], a.in[12], a.in[13], a.in[14], a.in[15], a.in[16], (f16*)(a.ws + WS_PG), (f16*)(a.ws + WS_QG), (f16*)(a.ws + WS_KTH)); );
.LBB0_230:
	s_cmp_lg_u32 s100, 0
	s_cbranch_scc1 .Lp1_stub_old
	s_cmpk_gt_i32 s81, 0x7f
	s_cbranch_scc1 .Lp1_stub_old
	s_mov_b32 s100, 7
	s_branch .LBB0_136
